# T12 extended to the cross-lane sum reductions in attention item epilogues (6 more sites)
# baseline (speedup 1.0000x reference)
; DI void attn_A(const Params& P, int l, int b, int head, int qt, float lam, char* smem, bf16_t* ybase, size_t ypitch) {
;     ...
;   l0 += __shfl_xor(l0, 16); l0 += __shfl_xor(l0, 32);
;   l1 += __shfl_xor(l1, 16); l1 += __shfl_xor(l1, 32);
;   const float i0 = 1.0f / l0, i1 = lam / l1;
;   float ss = 0.f;
; #pragma unroll
;   for (int dt = 0; dt < 8; ++dt)
; #pragma unroll
;     for (int j = 0; j < 4; ++j) { const float v = o0[dt][j] * i0 - o1[dt][j] * i1; o0[dt][j] = v; ss += v * v; }
;   ss += __shfl_xor(ss, 16); ss += __shfl_xor(ss, 32);
;   const float r = rsqrtf(ss * (1.0f / 128.0f) + EPS) * (1.0f - P.lam_init[l]);
;   const float* sg = P.a_subln + l * 128;
;   bf16_t* yp = ybase + tokq * ypitch + head * 128;
.LBB0_812:
	ds_bpermute_b32 v0, v189, v170
	v_lshlrev_b32_e32 v150, 3, v194
	s_waitcnt lgkmcnt(0)
	v_add_f32_e32 v0, v170, v0
	v_mov_b32_e32 v1, v0
	s_waitcnt lgkmcnt(0)
	s_nop 1
	v_permlane32_swap_b32_e32 v0, v1
	v_add_f32_e32 v0, v0, v1
	ds_bpermute_b32 v1, v189, v171
	s_waitcnt lgkmcnt(0)
	v_add_f32_e32 v1, v171, v1
	v_mov_b32_e32 v2, v1
	s_waitcnt lgkmcnt(0)
	s_nop 1
	v_permlane32_swap_b32_e32 v1, v2
	v_add_f32_e32 v1, v1, v2
	v_div_scale_f32 v2, s[4:5], v0, v0, 1.0
	v_rcp_f32_e32 v3, v2
	s_nop 0
	v_fma_f32 v4, -v2, v3, 1.0
	v_fmac_f32_e32 v3, v4, v3
	v_div_scale_f32 v4, vcc, 1.0, v0, 1.0
	v_mul_f32_e32 v5, v4, v3
	v_fma_f32 v6, -v2, v5, v4
	v_fmac_f32_e32 v5, v6, v3
	v_fma_f32 v2, -v2, v5, v4
	v_div_fmas_f32 v2, v2, v3, v5
	v_div_fixup_f32 v10, v2, v0, 1.0
	v_div_scale_f32 v0, s[4:5], v1, v1, v193
	v_rcp_f32_e32 v2, v0
	v_readlane_b32 s4, v252, 29
	v_readlane_b32 s5, v252, 30
	s_load_dword s1, s[4:5], 0x140
	v_fma_f32 v3, -v0, v2, 1.0
	v_fmac_f32_e32 v2, v3, v2
	v_div_scale_f32 v3, vcc, v193, v1, v193
	v_mul_f32_e32 v4, v3, v2
	v_fma_f32 v5, -v0, v4, v3
	v_fmac_f32_e32 v4, v5, v2
	v_fma_f32 v0, -v0, v4, v3
	v_div_fmas_f32 v0, v0, v2, v4
	v_div_fixup_f32 v12, v0, v1, v193
	v_readlane_b32 s4, v252, 31
	v_pk_mul_f32 v[6:7], v[102:103], v[12:13] op_sel_hi:[1,0]
	v_readlane_b32 s5, v252, 32
	s_waitcnt vmcnt(7)
	v_pk_fma_f32 v[18:19], v[94:95], v[10:11], v[6:7] op_sel_hi:[1,0,1] neg_lo:[0,0,1] neg_hi:[0,0,1]
	s_waitcnt vmcnt(5)
	v_pk_mul_f32 v[22:23], v[100:101], v[12:13] op_sel_hi:[1,0]
	v_pk_mul_f32 v[20:21], v[18:19], v[18:19]
	v_pk_fma_f32 v[22:23], v[92:93], v[10:11], v[22:23] op_sel_hi:[1,0,1] neg_lo:[0,0,1] neg_hi:[0,0,1]
	s_waitcnt vmcnt(4)
	v_pk_mul_f32 v[30:31], v[96:97], v[12:13] op_sel_hi:[1,0]
	global_load_dwordx4 v[6:9], v154, s[4:5]
	v_pk_mul_f32 v[24:25], v[22:23], v[22:23]
	v_pk_fma_f32 v[30:31], v[84:85], v[10:11], v[30:31] op_sel_hi:[1,0,1] neg_lo:[0,0,1] neg_hi:[0,0,1]
	v_add_f32_e32 v24, v24, v25
	v_add_f32_e32 v20, v20, v24
	v_pk_mul_f32 v[26:27], v[98:99], v[12:13] op_sel_hi:[1,0]
	s_waitcnt vmcnt(4)
	v_pk_mul_f32 v[32:33], v[30:31], v[30:31]
	v_add_f32_e32 v20, v21, v20
	v_pk_fma_f32 v[26:27], v[86:87], v[10:11], v[26:27] op_sel_hi:[1,0,1] neg_lo:[0,0,1] neg_hi:[0,0,1]
	v_add_f32_e32 v20, v32, v20
	v_pk_mul_f32 v[28:29], v[26:27], v[26:27]
	s_waitcnt vmcnt(3)
	v_pk_mul_f32 v[38:39], v[88:89], v[12:13] op_sel_hi:[1,0]
	v_add_f32_e32 v20, v33, v20
	v_pk_fma_f32 v[38:39], v[76:77], v[10:11], v[38:39] op_sel_hi:[1,0,1] neg_lo:[0,0,1] neg_hi:[0,0,1]
	v_add_f32_e32 v20, v28, v20
	v_pk_mul_f32 v[34:35], v[90:91], v[12:13] op_sel_hi:[1,0]
	s_waitcnt vmcnt(2)
	v_pk_mul_f32 v[52:53], v[38:39], v[38:39]
	v_add_f32_e32 v20, v29, v20
	v_pk_fma_f32 v[34:35], v[78:79], v[10:11], v[34:35] op_sel_hi:[1,0,1] neg_lo:[0,0,1] neg_hi:[0,0,1]
	v_add_f32_e32 v20, v52, v20
	v_pk_mul_f32 v[36:37], v[34:35], v[34:35]
	s_waitcnt vmcnt(1)
	v_pk_mul_f32 v[66:67], v[80:81], v[12:13] op_sel_hi:[1,0]
	v_add_f32_e32 v20, v53, v20
	v_pk_fma_f32 v[66:67], v[68:69], v[10:11], v[66:67] op_sel_hi:[1,0,1] neg_lo:[0,0,1] neg_hi:[0,0,1]
	v_add_f32_e32 v20, v36, v20
	v_pk_mul_f32 v[54:55], v[82:83], v[12:13] op_sel_hi:[1,0]
	v_pk_mul_f32 v[68:69], v[66:67], v[66:67]
	v_add_f32_e32 v20, v37, v20
	v_pk_fma_f32 v[54:55], v[70:71], v[10:11], v[54:55] op_sel_hi:[1,0,1] neg_lo:[0,0,1] neg_hi:[0,0,1]
	v_add_f32_e32 v20, v68, v20
	v_pk_mul_f32 v[64:65], v[54:55], v[54:55]
	v_pk_mul_f32 v[72:73], v[72:73], v[12:13] op_sel_hi:[1,0]
	v_add_f32_e32 v20, v69, v20
	v_pk_fma_f32 v[56:57], v[56:57], v[10:11], v[72:73] op_sel_hi:[1,0,1] neg_lo:[0,0,1] neg_hi:[0,0,1]
	v_add_f32_e32 v20, v64, v20
	v_pk_mul_f32 v[70:71], v[74:75], v[12:13] op_sel_hi:[1,0]
	v_pk_mul_f32 v[72:73], v[56:57], v[56:57]
	v_add_f32_e32 v20, v65, v20
	v_pk_fma_f32 v[58:59], v[58:59], v[10:11], v[70:71] op_sel_hi:[1,0,1] neg_lo:[0,0,1] neg_hi:[0,0,1]
	v_add_f32_e32 v20, v72, v20
	v_pk_mul_f32 v[70:71], v[58:59], v[58:59]
	v_pk_mul_f32 v[60:61], v[60:61], v[12:13] op_sel_hi:[1,0]
	v_add_f32_e32 v20, v73, v20
	v_pk_fma_f32 v[44:45], v[44:45], v[10:11], v[60:61] op_sel_hi:[1,0,1] neg_lo:[0,0,1] neg_hi:[0,0,1]
	v_add_f32_e32 v20, v70, v20
	v_pk_mul_f32 v[62:63], v[62:63], v[12:13] op_sel_hi:[1,0]
	v_pk_mul_f32 v[60:61], v[44:45], v[44:45]
	v_add_f32_e32 v20, v71, v20
	v_pk_mul_f32 v[0:1], v[108:109], v[12:13] op_sel_hi:[1,0]
	v_pk_fma_f32 v[46:47], v[46:47], v[10:11], v[62:63] op_sel_hi:[1,0,1] neg_lo:[0,0,1] neg_hi:[0,0,1]
	v_add_f32_e32 v20, v60, v20
	v_pk_fma_f32 v[4:5], v[104:105], v[10:11], v[0:1] op_sel_hi:[1,0,1] neg_lo:[0,0,1] neg_hi:[0,0,1]
	v_pk_mul_f32 v[0:1], v[110:111], v[12:13] op_sel_hi:[1,0]
	v_pk_mul_f32 v[62:63], v[46:47], v[46:47]
	v_pk_mul_f32 v[50:51], v[50:51], v[12:13] op_sel_hi:[1,0]
	v_pk_mul_f32 v[12:13], v[48:49], v[12:13] op_sel_hi:[1,0]
	v_add_f32_e32 v20, v61, v20
	v_pk_fma_f32 v[2:3], v[106:107], v[10:11], v[0:1] op_sel_hi:[1,0,1] neg_lo:[0,0,1] neg_hi:[0,0,1]
	v_pk_fma_f32 v[42:43], v[42:43], v[10:11], v[50:51] op_sel_hi:[1,0,1] neg_lo:[0,0,1] neg_hi:[0,0,1]
	v_pk_fma_f32 v[10:11], v[40:41], v[10:11], v[12:13] op_sel_hi:[1,0,1] neg_lo:[0,0,1] neg_hi:[0,0,1]
	v_add_f32_e32 v20, v62, v20
	v_pk_mul_f32 v[12:13], v[10:11], v[10:11]
	v_add_f32_e32 v20, v63, v20
	v_add_f32_e32 v12, v12, v20
	v_pk_mul_f32 v[50:51], v[42:43], v[42:43]
	v_add_f32_e32 v12, v13, v12
	v_add_f32_e32 v12, v50, v12
	v_pk_mul_f32 v[14:15], v[4:5], v[4:5]
	v_add_f32_e32 v12, v51, v12
	v_add_f32_e32 v12, v14, v12
	v_pk_mul_f32 v[16:17], v[2:3], v[2:3]
	v_add_f32_e32 v12, v15, v12
	v_add_f32_e32 v12, v16, v12
	v_add_f32_e32 v12, v17, v12
	v_mov_b32_e32 v13, v12
	s_waitcnt lgkmcnt(0)
; DI unsigned pack2(float lo, float hi) { f2_t v = {lo, hi}; h2_t b = __builtin_convertvector(v, h2_t); return __builtin_bit_cast(unsigned, b); }
; DI void attn_A(const Params& P, int l, int b, int head, int qt, float lam, char* smem, bf16_t* ybase, size_t ypitch) {
;     ...
;   ss += __shfl_xor(ss, 16); ss += __shfl_xor(ss, 32);
;   const float r = rsqrtf(ss * (1.0f / 128.0f) + EPS) * (1.0f - P.lam_init[l]);
;   const float* sg = P.a_subln + l * 128;
;   bf16_t* yp = ybase + tokq * ypitch + head * 128;
; #pragma unroll
;   for (int dt = 0; dt < 8; ++dt) {
;     const float4 gq = *(const float4*)(sg + dt * 16 + 4 * g);
;     *(uint2*)(yp + dt * 16 + 4 * g) = make_uint2(pack2(o0[dt][0] * r * gq.x, o0[dt][1] * r * gq.y), pack2(o0[dt][2] * r * gq.z, o0[dt][3] * r * gq.w));
;   }
	s_nop 1
	v_permlane16_swap_b32_e32 v12, v13
	v_sub_f32_e64 v104, 1.0, s1
	s_mov_b32 s1, 0x800000
	v_lshl_add_u64 v[0:1], v[156:157], 0, v[150:151]
	v_add_f32_e32 v12, v12, v13
	v_mov_b32_e32 v13, v12
	s_waitcnt lgkmcnt(0)
	s_nop 1
	v_permlane32_swap_b32_e32 v12, v13
	v_add_f32_e32 v12, v12, v13
	v_fmamk_f32 v12, v12, 0x3c000000, v179
	v_cmp_gt_f32_e32 vcc, s1, v12
	v_mul_f32_e32 v13, 0x4b800000, v12
	s_nop 0
	v_cndmask_b32_e32 v12, v12, v13, vcc
	v_rsq_f32_e32 v12, v12
	s_nop 0
	v_mul_f32_e32 v13, 0x45800000, v12
	v_cndmask_b32_e32 v12, v12, v13, vcc
	v_mul_f32_e32 v12, v104, v12
	v_pk_mul_f32 v[14:15], v[22:23], v[12:13] op_sel_hi:[1,0]
	v_pk_mul_f32 v[10:11], v[10:11], v[12:13] op_sel_hi:[1,0]
	s_waitcnt vmcnt(0)
	v_pk_mul_f32 v[6:7], v[6:7], v[14:15]
	v_pk_mul_f32 v[14:15], v[18:19], v[12:13] op_sel_hi:[1,0]
	v_cvt_pk_f16_f32 v6, v6, v7
	v_pk_mul_f32 v[8:9], v[8:9], v[14:15]
	v_pk_mul_f32 v[14:15], v[30:31], v[12:13] op_sel_hi:[1,0]
	v_cvt_pk_f16_f32 v7, v8, v9
	global_store_dwordx2 v[0:1], v[6:7], off
	global_load_dwordx4 v[6:9], v154, s[4:5] offset:64
	v_pk_mul_f32 v[4:5], v[4:5], v[12:13] op_sel_hi:[1,0]
	v_pk_mul_f32 v[2:3], v[2:3], v[12:13] op_sel_hi:[1,0]
	s_waitcnt vmcnt(0)
	v_pk_mul_f32 v[6:7], v[6:7], v[14:15]
	v_pk_mul_f32 v[14:15], v[26:27], v[12:13] op_sel_hi:[1,0]
	v_cvt_pk_f16_f32 v6, v6, v7
	v_pk_mul_f32 v[8:9], v[8:9], v[14:15]
	v_pk_mul_f32 v[14:15], v[38:39], v[12:13] op_sel_hi:[1,0]
	v_cvt_pk_f16_f32 v7, v8, v9
	global_store_dwordx2 v[0:1], v[6:7], off offset:32
	global_load_dwordx4 v[6:9], v154, s[4:5] offset:128
	s_waitcnt vmcnt(0)
	v_pk_mul_f32 v[6:7], v[6:7], v[14:15]
	v_pk_mul_f32 v[14:15], v[34:35], v[12:13] op_sel_hi:[1,0]
	v_cvt_pk_f16_f32 v6, v6, v7
	v_pk_mul_f32 v[8:9], v[8:9], v[14:15]
	v_pk_mul_f32 v[14:15], v[66:67], v[12:13] op_sel_hi:[1,0]
	v_cvt_pk_f16_f32 v7, v8, v9
	global_store_dwordx2 v[0:1], v[6:7], off offset:64
	global_load_dwordx4 v[6:9], v154, s[4:5] offset:192
	s_waitcnt vmcnt(0)
	v_pk_mul_f32 v[6:7], v[6:7], v[14:15]
	v_pk_mul_f32 v[14:15], v[54:55], v[12:13] op_sel_hi:[1,0]
	v_cvt_pk_f16_f32 v6, v6, v7
	v_pk_mul_f32 v[8:9], v[8:9], v[14:15]
	v_pk_mul_f32 v[14:15], v[56:57], v[12:13] op_sel_hi:[1,0]
	v_cvt_pk_f16_f32 v7, v8, v9
	global_store_dwordx2 v[0:1], v[6:7], off offset:96
	global_load_dwordx4 v[6:9], v154, s[4:5] offset:256
	s_waitcnt vmcnt(0)
	v_pk_mul_f32 v[6:7], v[6:7], v[14:15]
	v_pk_mul_f32 v[14:15], v[58:59], v[12:13] op_sel_hi:[1,0]
	v_cvt_pk_f16_f32 v6, v6, v7
	v_pk_mul_f32 v[8:9], v[8:9], v[14:15]
	v_pk_mul_f32 v[14:15], v[44:45], v[12:13] op_sel_hi:[1,0]
	v_cvt_pk_f16_f32 v7, v8, v9
	global_store_dwordx2 v[0:1], v[6:7], off offset:128
	global_load_dwordx4 v[6:9], v154, s[4:5] offset:320
	s_waitcnt vmcnt(0)
	v_pk_mul_f32 v[6:7], v[6:7], v[14:15]
	v_pk_mul_f32 v[14:15], v[46:47], v[12:13] op_sel_hi:[1,0]
	v_cvt_pk_f16_f32 v6, v6, v7
	v_pk_mul_f32 v[8:9], v[8:9], v[14:15]
	s_nop 0
	v_cvt_pk_f16_f32 v7, v8, v9
	global_store_dwordx2 v[0:1], v[6:7], off offset:160
	global_load_dwordx4 v[6:9], v154, s[4:5] offset:384
	s_waitcnt vmcnt(0)
	v_pk_mul_f32 v[6:7], v[6:7], v[10:11]
	v_pk_mul_f32 v[10:11], v[42:43], v[12:13] op_sel_hi:[1,0]
	v_cvt_pk_f16_f32 v6, v6, v7
	v_pk_mul_f32 v[8:9], v[8:9], v[10:11]
	s_nop 0
	v_cvt_pk_f16_f32 v7, v8, v9
	global_store_dwordx2 v[0:1], v[6:7], off offset:192
	global_load_dwordx4 v[6:9], v154, s[4:5] offset:448
	s_waitcnt vmcnt(0)
	v_pk_mul_f32 v[4:5], v[6:7], v[4:5]
	v_pk_mul_f32 v[2:3], v[2:3], v[8:9]
	v_cvt_pk_f16_f32 v4, v4, v5
	v_cvt_pk_f16_f32 v5, v2, v3
	global_store_dwordx2 v[0:1], v[4:5], off offset:224

; DI unsigned pack2(float lo, float hi) { f2_t v = {lo, hi}; h2_t b = __builtin_convertvector(v, h2_t); return __builtin_bit_cast(unsigned, b); }
; DI void attn_C2x(const Params& P, int b, int head, int qp, char* smem, bf16_t* ybase, size_t ypitch) {
;     ...
;   la += __shfl_xor(la, 16); la += __shfl_xor(la, 32);
;   lb += __shfl_xor(lb, 16); lb += __shfl_xor(lb, 32);
;   const float ia = 1.0f / la, ib = 1.0f / lb;
;   bf16_t* ypa = ybase + tok0 * ypitch + head * 64;
;   bf16_t* ypb = ybase + (tok0 + 16) * ypitch + head * 64;
; #pragma unroll
;   for (int dt = 0; dt < 4; ++dt) {
;     *(uint2*)(ypa + dt * 16 + 4 * g) = make_uint2(pack2(oa[dt][0] * ia, oa[dt][1] * ia), pack2(oa[dt][2] * ia, oa[dt][3] * ia));
;     *(uint2*)(ypb + dt * 16 + 4 * g) = make_uint2(pack2(ob[dt][0] * ib, ob[dt][1] * ib), pack2(ob[dt][2] * ib, ob[dt][3] * ib));
;   }
.LBB0_1068:
	ds_bpermute_b32 v0, v189, v118
	s_lshl_b32 s26, s2, 1
	v_lshlrev_b32_e32 v150, 1, v132
	s_mov_b32 s1, 0x33000
	v_readlane_b32 s22, v254, 49
	s_waitcnt lgkmcnt(0)
	v_add_f32_e32 v0, v118, v0
	v_mov_b32_e32 v1, v0
	s_movk_i32 s23, 0x70
	s_mov_b32 s24, 0x1ffffc0
	s_mov_b32 s20, 0x100000
	s_waitcnt lgkmcnt(0)
	s_nop 1
	v_permlane32_swap_b32_e32 v0, v1
	v_add_f32_e32 v0, v0, v1
	ds_bpermute_b32 v1, v189, v119
	s_waitcnt lgkmcnt(0)
	v_add_f32_e32 v1, v119, v1
	v_mov_b32_e32 v2, v1
	s_waitcnt lgkmcnt(0)
	s_nop 1
	v_permlane32_swap_b32_e32 v1, v2
	v_add_f32_e32 v1, v1, v2
	v_div_scale_f32 v2, s[6:7], v0, v0, 1.0
	v_rcp_f32_e32 v3, v2
	s_nop 0
	v_fma_f32 v4, -v2, v3, 1.0
	v_fmac_f32_e32 v3, v4, v3
	v_div_scale_f32 v4, vcc, 1.0, v0, 1.0
	v_mul_f32_e32 v5, v4, v3
	v_fma_f32 v6, -v2, v5, v4
	v_fmac_f32_e32 v5, v6, v3
	v_fma_f32 v2, -v2, v5, v4
	v_div_fmas_f32 v2, v2, v3, v5
	v_div_fixup_f32 v0, v2, v0, 1.0
	v_div_scale_f32 v2, s[6:7], v1, v1, 1.0
	v_rcp_f32_e32 v3, v2
	v_readlane_b32 s6, v254, 37
	v_readlane_b32 s7, v254, 38
	v_pk_mul_f32 v[8:9], v[60:61], v[0:1] op_sel_hi:[1,0]
	v_fma_f32 v4, -v2, v3, 1.0
	v_fmac_f32_e32 v3, v4, v3
	v_div_scale_f32 v4, vcc, 1.0, v1, 1.0
	v_mul_f32_e32 v5, v4, v3
	v_fma_f32 v6, -v2, v5, v4
	v_fmac_f32_e32 v5, v6, v3
	v_fma_f32 v2, -v2, v5, v4
	v_div_fmas_f32 v2, v2, v3, v5
	v_lshl_add_u64 v[4:5], s[6:7], 0, v[104:105]
	v_lshl_add_u64 v[4:5], v[4:5], 0, s[26:27]
	v_pk_mul_f32 v[10:11], v[62:63], v[0:1] op_sel_hi:[1,0]
	v_div_fixup_f32 v2, v2, v1, 1.0
	v_lshl_add_u64 v[4:5], v[4:5], 0, v[150:151]
	v_cvt_pk_f16_f32 v8, v8, v9
	v_cvt_pk_f16_f32 v9, v10, v11
	global_store_dwordx2 v[4:5], v[8:9], off
	v_pk_mul_f32 v[8:9], v[56:57], v[2:3] op_sel_hi:[1,0]
	v_pk_mul_f32 v[10:11], v[58:59], v[2:3] op_sel_hi:[1,0]
	v_cvt_pk_f16_f32 v8, v8, v9
	v_cvt_pk_f16_f32 v9, v10, v11
	v_add_co_u32_e32 v10, vcc, s1, v4
	s_mov_b64 s[6:7], 0x33000
	s_nop 0
	v_addc_co_u32_e32 v11, vcc, 0, v5, vcc
	global_store_dwordx2 v[10:11], v[8:9], off
	v_pk_mul_f32 v[8:9], v[68:69], v[0:1] op_sel_hi:[1,0]
	v_pk_mul_f32 v[10:11], v[70:71], v[0:1] op_sel_hi:[1,0]
	v_cvt_pk_f16_f32 v8, v8, v9
	v_cvt_pk_f16_f32 v9, v10, v11
	global_store_dwordx2 v[4:5], v[8:9], off offset:32
	v_pk_mul_f32 v[8:9], v[64:65], v[2:3] op_sel_hi:[1,0]
	v_pk_mul_f32 v[10:11], v[66:67], v[2:3] op_sel_hi:[1,0]
	v_lshl_add_u64 v[6:7], v[4:5], 0, s[6:7]
	v_cvt_pk_f16_f32 v8, v8, v9
	v_cvt_pk_f16_f32 v9, v10, v11
	global_store_dwordx2 v[6:7], v[8:9], off offset:32
	v_pk_mul_f32 v[8:9], v[52:53], v[0:1] op_sel_hi:[1,0]
	v_pk_mul_f32 v[10:11], v[54:55], v[0:1] op_sel_hi:[1,0]
	v_cvt_pk_f16_f32 v8, v8, v9
	v_cvt_pk_f16_f32 v9, v10, v11
	global_store_dwordx2 v[4:5], v[8:9], off offset:64
	v_pk_mul_f32 v[8:9], v[48:49], v[2:3] op_sel_hi:[1,0]
	v_pk_mul_f32 v[10:11], v[50:51], v[2:3] op_sel_hi:[1,0]
	v_cvt_pk_f16_f32 v8, v8, v9
	v_cvt_pk_f16_f32 v9, v10, v11
	global_store_dwordx2 v[6:7], v[8:9], off offset:64
	v_pk_mul_f32 v[8:9], v[72:73], v[0:1] op_sel_hi:[1,0]
	v_pk_mul_f32 v[0:1], v[74:75], v[0:1] op_sel_hi:[1,0]
	v_cvt_pk_f16_f32 v8, v8, v9
	v_cvt_pk_f16_f32 v9, v0, v1
	v_pk_mul_f32 v[0:1], v[76:77], v[2:3] op_sel_hi:[1,0]
	v_pk_mul_f32 v[2:3], v[78:79], v[2:3] op_sel_hi:[1,0]
	v_cvt_pk_f16_f32 v0, v0, v1
	v_cvt_pk_f16_f32 v1, v2, v3
	s_mov_b64 s[6:7], 0
	global_store_dwordx2 v[4:5], v[8:9], off offset:96
	global_store_dwordx2 v[6:7], v[0:1], off offset:96
